# stack23 + all seams release by polling the global arrival counter; seam 2 (P2->P3) split: workgroups arrive before their short-conv work and wait after it (conv output is not consumed before P5), PARK
# speedup vs baseline: 1.0038x; 1.0032x over previous
.LBB0_99:
	s_or_b64 exec, exec, s[10:11]
	v_cvt_f32_u32_e32 v6, v4
	s_waitcnt vmcnt(0)
	v_readfirstlane_b32 s0, v5
	v_sub_u32_e32 v5, 0, v4
	v_rcp_iflag_f32_e32 v6, v6
	v_add_u32_e32 v7, s0, v3
	v_mul_f32_e32 v6, 0x4f7ffffe, v6
	v_cvt_u32_f32_e32 v6, v6
	v_mul_lo_u32 v3, v5, v6
	v_mul_hi_u32 v3, v6, v3
	v_add_u32_e32 v3, v6, v3
	v_mul_hi_u32 v3, v7, v3
	v_mul_lo_u32 v5, v3, v4
	v_sub_u32_e32 v5, v7, v5
	v_add_u32_e32 v6, 1, v3
	v_cmp_ge_u32_e32 vcc, v5, v4
	s_nop 1
	v_cndmask_b32_e32 v3, v3, v6, vcc
	v_sub_u32_e32 v6, v5, v4
	v_cndmask_b32_e32 v5, v5, v6, vcc
	v_add_u32_e32 v6, 1, v3
	v_cmp_ge_u32_e32 vcc, v5, v4
	v_add_u32_e32 v5, 1, v7
	s_nop 0
	v_cndmask_b32_e32 v3, v3, v6, vcc
	v_mul_lo_u32 v6, v4, v3
	v_add_u32_e32 v4, v6, v4
	v_cmp_ne_u32_e32 vcc, v5, v4
	s_and_saveexec_b64 s[0:1], vcc
	s_xor_b64 s[8:9], exec, s[0:1]
	s_cbranch_execz .LBB0_113
	s_waitcnt lgkmcnt(0)
	v_add_u32_e32 v249, 1, v3
	v_mul_lo_u32 v249, v249, v2
	s_add_u32 s98, s76, 0x3400
	s_addc_u32 s99, s77, 0
	v_mov_b32_e32 v2, 0
	global_load_dword v2, v2, s[98:99] sc1
	s_add_u32 s12, s6, 0x2400
	s_addc_u32 s13, s7, 0
	s_waitcnt vmcnt(0)
	v_cmp_lt_u32_e32 vcc, v2, v249
	s_and_saveexec_b64 s[10:11], vcc
	s_cbranch_execz .LBB0_112
	s_mov_b32 s0, 1
	s_mov_b64 s[14:15], 0
	v_mov_b32_e32 v2, 0
	s_branch .LBB0_103

.LBB0_105:
	global_load_dword v4, v2, s[98:99] sc1
	s_add_i32 s0, s0, 1
	s_mov_b64 s[20:21], -1
	s_waitcnt vmcnt(0)
	v_cmp_ge_u32_e32 vcc, v4, v249
	s_orn2_b64 s[18:19], vcc, exec
	s_branch .LBB0_102

.LBB0_504:
	s_add_i32 s0, s79, -1
	s_cmp_lg_u32 s78, s0
	s_cbranch_scc1 .Lsp2_nopark
	s_waitcnt vmcnt(0)
	v_lshlrev_b32_e32 v2, 7, v0
	v_and_b32_e32 v2, 0x8000, v2
	v_mov_b32_e32 v3, 0
	v_lshl_add_u64 v[4:5], s[76:77], 0, v[2:3]
	v_mov_b32_e32 v2, 2
	v_lshlrev_b32_sdwa v2, v2, v0 dst_sel:DWORD dst_unused:UNUSED_PAD src0_sel:DWORD src1_sel:BYTE_0
	v_lshl_add_u64 v[4:5], v[4:5], 0, v[2:3]
	s_mov_b64 s[0:1], 0x8923400
	v_lshl_add_u64 v[6:7], v[4:5], 0, s[0:1]
	s_mov_b32 s0, 0x8923000
	v_add_co_u32_e32 v8, vcc, s0, v4
	s_mov_b32 s0, 0x8924000
	s_nop 0
	v_addc_co_u32_e32 v9, vcc, 0, v5, vcc
	v_add_co_u32_e32 v10, vcc, s0, v4
	s_mov_b32 s0, 0x8925000
	s_nop 0
	v_addc_co_u32_e32 v11, vcc, 0, v5, vcc
	v_add_co_u32_e32 v12, vcc, s0, v4
	s_mov_b32 s0, 0x8926000
	s_nop 0
	v_addc_co_u32_e32 v13, vcc, 0, v5, vcc
	global_load_dword v14, v[8:9], off offset:1024
	global_load_dword v15, v[6:7], off offset:1024
	global_load_dword v16, v[6:7], off offset:2048
	global_load_dword v17, v[10:11], off offset:1024
	global_load_dword v18, v[10:11], off offset:2048
	global_load_dword v19, v[10:11], off offset:3072
	global_load_dword v20, v[12:13], off offset:1024
	global_load_dword v21, v[6:7], off offset:3072
	v_add_co_u32_e32 v6, vcc, s0, v4
	s_mov_b32 s0, 0x8927000
	s_nop 0
	v_addc_co_u32_e32 v7, vcc, 0, v5, vcc
	global_load_dword v22, v[12:13], off offset:2048
	global_load_dword v23, v[12:13], off offset:3072
	v_add_co_u32_e32 v8, vcc, s0, v4
	s_mov_b32 s0, 0x8928000
	s_nop 0
	v_addc_co_u32_e32 v9, vcc, 0, v5, vcc
	v_add_co_u32_e32 v10, vcc, s0, v4
	s_mov_b32 s0, 0x8929000
	s_nop 0
	v_addc_co_u32_e32 v11, vcc, 0, v5, vcc
	global_load_dword v24, v[6:7], off offset:-4096
	global_load_dword v25, v[6:7], off
	global_load_dword v26, v[6:7], off offset:1024
	global_load_dword v27, v[6:7], off offset:2048
	global_load_dword v28, v[6:7], off offset:3072
	global_load_dword v29, v[10:11], off offset:-4096
	global_load_dword v30, v[10:11], off
	v_add_co_u32_e32 v6, vcc, s0, v4
	s_mov_b32 s0, 0x892a000
	s_nop 0
	v_addc_co_u32_e32 v7, vcc, 0, v5, vcc
	v_add_co_u32_e32 v12, vcc, s0, v4
	v_lshlrev_b32_e32 v2, 2, v0
	s_nop 0
	v_addc_co_u32_e32 v13, vcc, 0, v5, vcc
	global_load_dword v31, v[8:9], off offset:1024
	global_load_dword v32, v[8:9], off offset:2048
	global_load_dword v33, v[8:9], off offset:3072
	global_load_dword v34, v[6:7], off offset:1024
	global_load_dword v35, v[6:7], off offset:2048
	global_load_dword v36, v[6:7], off offset:3072
	global_load_dword v37, v[10:11], off offset:1024
	global_load_dword v38, v[10:11], off offset:2048
	global_load_dword v39, v[10:11], off offset:3072
	global_load_dword v40, v[12:13], off offset:-4096
	global_load_dword v41, v[12:13], off
	global_load_dword v42, v[12:13], off offset:1024
	global_load_dword v43, v[12:13], off offset:2048
	global_load_dword v44, v[12:13], off offset:3072
	v_add_co_u32_e32 v4, vcc, 0x892b000, v4
	v_lshl_add_u64 v[2:3], s[76:77], 0, v[2:3]
	s_nop 0
	v_addc_co_u32_e32 v5, vcc, 0, v5, vcc
	global_load_dword v4, v[4:5], off
	v_add_co_u32_e32 v2, vcc, 0x1ce33000, v2
	s_waitcnt vmcnt(31)
	v_add_f32_e32 v5, 0, v14
	s_waitcnt vmcnt(30)
	v_add_f32_e32 v5, v5, v15
	s_waitcnt vmcnt(29)
	v_add_f32_e32 v5, v5, v16
	v_addc_co_u32_e32 v3, vcc, 0, v3, vcc
	s_waitcnt vmcnt(24)
	v_add_f32_e32 v5, v5, v21
	v_add_f32_e32 v5, v5, v17
	v_add_f32_e32 v5, v5, v18
	v_add_f32_e32 v5, v5, v19
	s_waitcnt vmcnt(21)
	v_add_f32_e32 v5, v5, v24
	v_add_f32_e32 v5, v5, v20
	v_add_f32_e32 v5, v5, v22
	v_add_f32_e32 v5, v5, v23
	s_waitcnt vmcnt(20)
	v_add_f32_e32 v5, v5, v25
	s_waitcnt vmcnt(19)
	v_add_f32_e32 v5, v5, v26
	s_waitcnt vmcnt(18)
	v_add_f32_e32 v5, v5, v27
	s_waitcnt vmcnt(17)
	v_add_f32_e32 v5, v5, v28
	s_waitcnt vmcnt(16)
	v_add_f32_e32 v5, v5, v29
	s_waitcnt vmcnt(14)
	v_add_f32_e32 v5, v5, v31
	s_waitcnt vmcnt(13)
	v_add_f32_e32 v5, v5, v32
	s_waitcnt vmcnt(12)
	v_add_f32_e32 v5, v5, v33
	v_add_f32_e32 v5, v5, v30
	s_waitcnt vmcnt(8)
	v_add_f32_e32 v5, v5, v37
	s_waitcnt vmcnt(7)
	v_add_f32_e32 v5, v5, v38
	s_waitcnt vmcnt(6)
	v_add_f32_e32 v5, v5, v39
	s_waitcnt vmcnt(5)
	v_add_f32_e32 v5, v5, v40
	v_add_f32_e32 v5, v5, v34
	v_add_f32_e32 v5, v5, v35
	v_add_f32_e32 v5, v5, v36
	s_waitcnt vmcnt(4)
	v_add_f32_e32 v5, v5, v41
	s_waitcnt vmcnt(3)
	v_add_f32_e32 v5, v5, v42
	s_waitcnt vmcnt(2)
	v_add_f32_e32 v5, v5, v43
	s_waitcnt vmcnt(1)
	v_add_f32_e32 v5, v5, v44
	s_waitcnt vmcnt(0)
	v_add_f32_e32 v4, v5, v4
	global_store_dword v[2:3], v4, off offset:1024
.Lsp2_nopark:
	s_cmp_gt_i32 s89, 3
	s_cbranch_scc0 .Lsp2_noarrive
	s_waitcnt vmcnt(0) lgkmcnt(0)
	s_barrier
	v_cmp_eq_u32_e32 vcc, 0, v0
	s_and_saveexec_b64 s[98:99], vcc
	s_cbranch_execz .Lsp2_arrived
	v_mov_b32_e32 v248, 0x23e20
	ds_read_b32 v249, v248
	ds_read_b32 v250, v248 offset:4
	v_mov_b32_e32 v251, s82
	v_lshlrev_b32_e32 v251, 8, v251
	v_add_u32_e32 v251, 0x1400, v251
	v_mov_b32_e32 v252, 1
	global_atomic_add v253, v251, v252, s[76:77] sc0
	s_waitcnt lgkmcnt(0)
	v_cvt_f32_u32_e32 v254, v249
	v_rcp_iflag_f32_e32 v254, v254
	v_sub_u32_e32 v255, 0, v249
	s_nop 0
	v_mul_f32_e32 v254, 0x4f7ffffe, v254
	v_cvt_u32_f32_e32 v254, v254
	v_mul_lo_u32 v255, v255, v254
	v_mul_hi_u32 v255, v254, v255
	v_add_u32_e32 v254, v254, v255
	s_waitcnt vmcnt(0)
	v_mul_hi_u32 v255, v253, v254
	v_mul_lo_u32 v252, v255, v249
	v_sub_u32_e32 v252, v253, v252
	v_add_u32_e32 v248, 1, v255
	v_cmp_ge_u32_e32 vcc, v252, v249
	s_nop 1
	v_cndmask_b32_e32 v255, v255, v248, vcc
	v_sub_u32_e32 v248, v252, v249
	v_cndmask_b32_e32 v252, v252, v248, vcc
	v_add_u32_e32 v248, 1, v255
	v_cmp_ge_u32_e32 vcc, v252, v249
	s_nop 1
	v_cndmask_b32_e32 v255, v255, v248, vcc
	v_add_u32_e32 v248, 1, v255
	v_mul_lo_u32 v252, v248, v250
	v_mul_lo_u32 v254, v248, v249
	v_add_u32_e32 v253, 1, v253
	s_nop 0
	v_readfirstlane_b32 s101, v252
	v_cmp_eq_u32_e32 vcc, v253, v254
	s_cbranch_vccz .Lsp2_arrived
	buffer_wbl2 sc1
	s_waitcnt vmcnt(0)
	v_mov_b32_e32 v251, 0x3400
	v_mov_b32_e32 v252, 1
	global_atomic_add v251, v252, s[76:77]
	v_mov_b32_e32 v251, s82
	v_lshlrev_b32_e32 v251, 8, v251
	v_add_u32_e32 v251, 0x2400, v251
	global_atomic_add v251, v252, s[76:77]
.Lsp2_arrived:
	s_or_b64 exec, exec, s[98:99]

.LBB0_512:
	s_or_b64 exec, exec, s[2:3]
	v_lshl_add_u64 v[134:135], v[98:99], 0, v[102:103]
	v_lshl_add_u64 v[102:103], v[98:99], 0, v[118:119]
	s_waitcnt vmcnt(0)
	v_pk_mul_f32 v[118:119], v[18:19], v[120:121]
	v_lshl_add_u64 v[138:139], v[98:99], 0, v[106:107]
	v_lshl_add_u64 v[106:107], v[98:99], 0, v[110:111]
	v_lshlrev_b32_e32 v110, 16, v94
	v_and_b32_e32 v111, 0xffff0000, v94
	v_pk_fma_f32 v[118:119], v[30:31], v[132:133], v[118:119]
	v_lshl_add_u64 v[136:137], v[98:99], 0, v[104:105]
	v_pk_fma_f32 v[118:119], v[22:23], v[110:111], v[118:119]
	v_lshl_add_u64 v[104:105], v[98:99], 0, v[114:115]
	v_lshlrev_b32_e32 v114, 16, v90
	v_and_b32_e32 v115, 0xffff0000, v90
	v_pk_add_f32 v[118:119], v[26:27], v[118:119]
	v_lshl_add_u64 v[100:101], v[98:99], 0, v[122:123]
	v_pk_mul_f32 v[114:115], v[118:119], v[114:115]
	v_pk_mul_f32 v[118:119], v[20:21], v[116:117]
	v_lshl_add_u64 v[98:99], v[98:99], 0, v[124:125]
	v_lshlrev_b32_e32 v94, 16, v95
	v_and_b32_e32 v95, 0xffff0000, v95
	v_pk_fma_f32 v[118:119], v[32:33], v[130:131], v[118:119]
	v_pk_mul_f32 v[124:125], v[6:7], v[112:113]
	v_pk_fma_f32 v[118:119], v[24:25], v[94:95], v[118:119]
	v_lshlrev_b32_e32 v122, 16, v96
	v_and_b32_e32 v123, 0xffff0000, v96
	v_pk_fma_f32 v[124:125], v[10:11], v[128:129], v[124:125]
	v_lshlrev_b32_e32 v90, 16, v91
	v_and_b32_e32 v91, 0xffff0000, v91
	v_pk_add_f32 v[118:119], v[28:29], v[118:119]
	v_pk_fma_f32 v[124:125], v[2:3], v[122:123], v[124:125]
	v_pk_mul_f32 v[118:119], v[118:119], v[90:91]
	v_lshlrev_b32_e32 v90, 16, v92
	v_and_b32_e32 v91, 0xffff0000, v92
	v_pk_add_f32 v[124:125], v[14:15], v[124:125]
	v_lshlrev_b32_e32 v96, 16, v97
	v_pk_mul_f32 v[124:125], v[124:125], v[90:91]
	v_lshlrev_b32_e32 v90, 16, v93
	v_and_b32_e32 v91, 0xffff0000, v93
	v_pk_mul_f32 v[92:93], v[8:9], v[108:109]
	v_and_b32_e32 v97, 0xffff0000, v97
	v_pk_fma_f32 v[92:93], v[12:13], v[126:127], v[92:93]
	v_pk_mul_f32 v[112:113], v[10:11], v[112:113]
	v_pk_fma_f32 v[92:93], v[4:5], v[96:97], v[92:93]
	v_pk_fma_f32 v[112:113], v[6:7], v[122:123], v[112:113]
	v_pk_add_f32 v[92:93], v[16:17], v[92:93]
	s_nop 0
	v_pk_mul_f32 v[126:127], v[92:93], v[90:91]
	v_cvt_pk_bf16_f32 v90, v114, v115
	v_cvt_pk_bf16_f32 v91, v118, v119
	v_cvt_pk_bf16_f32 v92, v124, v125
	v_cvt_pk_bf16_f32 v93, v126, v127
	v_pk_mul_f32 v[114:115], v[30:31], v[120:121]
	global_store_dwordx4 v[134:135], v[90:93], off
	v_pk_fma_f32 v[114:115], v[18:19], v[110:111], v[114:115]
	s_nop 0
	v_lshlrev_b32_e32 v90, 16, v86
	v_and_b32_e32 v91, 0xffff0000, v86
	v_pk_fma_f32 v[114:115], v[22:23], v[90:91], v[114:115]
	v_lshlrev_b32_e32 v92, 16, v82
	v_and_b32_e32 v93, 0xffff0000, v82
	v_pk_add_f32 v[114:115], v[26:27], v[114:115]
	v_lshlrev_b32_e32 v86, 16, v87
	v_pk_mul_f32 v[92:93], v[114:115], v[92:93]
	v_pk_mul_f32 v[114:115], v[32:33], v[116:117]
	v_and_b32_e32 v87, 0xffff0000, v87
	v_pk_fma_f32 v[114:115], v[20:21], v[94:95], v[114:115]
	v_lshlrev_b32_e32 v116, 16, v88
	v_pk_fma_f32 v[114:115], v[24:25], v[86:87], v[114:115]
	v_and_b32_e32 v117, 0xffff0000, v88
	v_lshlrev_b32_e32 v82, 16, v83
	v_and_b32_e32 v83, 0xffff0000, v83
	v_pk_add_f32 v[114:115], v[28:29], v[114:115]
	v_pk_fma_f32 v[112:113], v[2:3], v[116:117], v[112:113]
	v_pk_mul_f32 v[114:115], v[114:115], v[82:83]
	v_lshlrev_b32_e32 v82, 16, v84
	v_and_b32_e32 v83, 0xffff0000, v84
	v_pk_add_f32 v[112:113], v[14:15], v[112:113]
	v_lshlrev_b32_e32 v88, 16, v89
	v_pk_mul_f32 v[112:113], v[112:113], v[82:83]
	v_lshlrev_b32_e32 v82, 16, v85
	v_and_b32_e32 v83, 0xffff0000, v85
	v_pk_mul_f32 v[84:85], v[12:13], v[108:109]
	v_and_b32_e32 v89, 0xffff0000, v89
	v_pk_fma_f32 v[84:85], v[8:9], v[96:97], v[84:85]
	s_nop 0
	v_pk_fma_f32 v[84:85], v[4:5], v[88:89], v[84:85]
	s_nop 0
	v_pk_add_f32 v[84:85], v[16:17], v[84:85]
	s_nop 0
	v_pk_mul_f32 v[108:109], v[84:85], v[82:83]
	v_cvt_pk_bf16_f32 v82, v92, v93
	v_cvt_pk_bf16_f32 v83, v114, v115
	v_cvt_pk_bf16_f32 v84, v112, v113
	v_cvt_pk_bf16_f32 v85, v108, v109
	v_pk_mul_f32 v[92:93], v[18:19], v[90:91]
	global_store_dwordx4 v[136:137], v[82:85], off
	v_pk_fma_f32 v[92:93], v[30:31], v[110:111], v[92:93]
	v_pk_mul_f32 v[108:109], v[6:7], v[116:117]
	v_lshlrev_b32_e32 v82, 16, v78
	v_and_b32_e32 v83, 0xffff0000, v78
	v_pk_fma_f32 v[92:93], v[22:23], v[82:83], v[92:93]
	v_lshlrev_b32_e32 v84, 16, v74
	v_and_b32_e32 v85, 0xffff0000, v74
	v_pk_add_f32 v[92:93], v[26:27], v[92:93]
	v_lshlrev_b32_e32 v78, 16, v79
	v_pk_mul_f32 v[84:85], v[92:93], v[84:85]
	v_pk_mul_f32 v[92:93], v[20:21], v[86:87]
	v_and_b32_e32 v79, 0xffff0000, v79
	v_pk_fma_f32 v[92:93], v[32:33], v[94:95], v[92:93]
	v_lshlrev_b32_e32 v94, 16, v80
	v_pk_fma_f32 v[92:93], v[24:25], v[78:79], v[92:93]
	v_and_b32_e32 v95, 0xffff0000, v80
	v_pk_fma_f32 v[108:109], v[10:11], v[122:123], v[108:109]
	v_lshlrev_b32_e32 v74, 16, v75
	v_and_b32_e32 v75, 0xffff0000, v75
	v_pk_add_f32 v[92:93], v[28:29], v[92:93]
	v_pk_fma_f32 v[108:109], v[2:3], v[94:95], v[108:109]
	v_pk_mul_f32 v[92:93], v[92:93], v[74:75]
	v_lshlrev_b32_e32 v74, 16, v76
	v_and_b32_e32 v75, 0xffff0000, v76
	v_pk_add_f32 v[108:109], v[14:15], v[108:109]
	v_lshlrev_b32_e32 v80, 16, v81
	v_pk_mul_f32 v[108:109], v[108:109], v[74:75]
	v_lshlrev_b32_e32 v74, 16, v77
	v_and_b32_e32 v75, 0xffff0000, v77
	v_pk_mul_f32 v[76:77], v[8:9], v[88:89]
	v_and_b32_e32 v81, 0xffff0000, v81
	v_pk_fma_f32 v[76:77], v[12:13], v[96:97], v[76:77]
	s_nop 0
	v_pk_fma_f32 v[76:77], v[4:5], v[80:81], v[76:77]
	s_nop 0
	v_pk_add_f32 v[76:77], v[16:17], v[76:77]
	s_nop 0
	v_pk_mul_f32 v[96:97], v[76:77], v[74:75]
	v_cvt_pk_bf16_f32 v74, v84, v85
	v_cvt_pk_bf16_f32 v75, v92, v93
	v_cvt_pk_bf16_f32 v76, v108, v109
	v_cvt_pk_bf16_f32 v77, v96, v97
	v_pk_mul_f32 v[84:85], v[18:19], v[82:83]
	global_store_dwordx4 v[138:139], v[74:77], off
	v_pk_fma_f32 v[84:85], v[30:31], v[90:91], v[84:85]
	v_pk_mul_f32 v[90:91], v[6:7], v[94:95]
	v_lshlrev_b32_e32 v74, 16, v70
	v_and_b32_e32 v75, 0xffff0000, v70
	v_pk_fma_f32 v[84:85], v[22:23], v[74:75], v[84:85]
	v_lshlrev_b32_e32 v76, 16, v66
	v_and_b32_e32 v77, 0xffff0000, v66
	v_pk_add_f32 v[84:85], v[26:27], v[84:85]
	v_lshlrev_b32_e32 v70, 16, v71
	v_pk_mul_f32 v[76:77], v[84:85], v[76:77]
	v_pk_mul_f32 v[84:85], v[20:21], v[78:79]
	v_and_b32_e32 v71, 0xffff0000, v71
	v_pk_fma_f32 v[84:85], v[32:33], v[86:87], v[84:85]
	v_lshlrev_b32_e32 v86, 16, v72
	v_pk_fma_f32 v[84:85], v[24:25], v[70:71], v[84:85]
	v_and_b32_e32 v87, 0xffff0000, v72
	v_pk_fma_f32 v[90:91], v[10:11], v[116:117], v[90:91]
	v_lshlrev_b32_e32 v66, 16, v67
	v_and_b32_e32 v67, 0xffff0000, v67
	v_pk_add_f32 v[84:85], v[28:29], v[84:85]
	v_pk_fma_f32 v[90:91], v[2:3], v[86:87], v[90:91]
	v_pk_mul_f32 v[84:85], v[84:85], v[66:67]
	v_lshlrev_b32_e32 v66, 16, v68
	v_and_b32_e32 v67, 0xffff0000, v68
	v_pk_add_f32 v[90:91], v[14:15], v[90:91]
	v_lshlrev_b32_e32 v72, 16, v73
	v_pk_mul_f32 v[90:91], v[90:91], v[66:67]
	v_lshlrev_b32_e32 v66, 16, v69
	v_and_b32_e32 v67, 0xffff0000, v69
	v_pk_mul_f32 v[68:69], v[8:9], v[80:81]
	v_and_b32_e32 v73, 0xffff0000, v73
	v_pk_fma_f32 v[68:69], v[12:13], v[88:89], v[68:69]
	s_nop 0
	v_pk_fma_f32 v[68:69], v[4:5], v[72:73], v[68:69]
	s_nop 0
	v_pk_add_f32 v[68:69], v[16:17], v[68:69]
	s_nop 0
	v_pk_mul_f32 v[88:89], v[68:69], v[66:67]
	v_cvt_pk_bf16_f32 v66, v76, v77
	v_cvt_pk_bf16_f32 v67, v84, v85
	v_cvt_pk_bf16_f32 v68, v90, v91
	v_cvt_pk_bf16_f32 v69, v88, v89
	v_pk_mul_f32 v[76:77], v[18:19], v[74:75]
	global_store_dwordx4 v[106:107], v[66:69], off
	v_pk_fma_f32 v[76:77], v[30:31], v[82:83], v[76:77]
	v_pk_mul_f32 v[82:83], v[6:7], v[86:87]
	v_lshlrev_b32_e32 v66, 16, v62
	v_and_b32_e32 v67, 0xffff0000, v62
	v_pk_fma_f32 v[76:77], v[22:23], v[66:67], v[76:77]
	v_lshlrev_b32_e32 v68, 16, v58
	v_and_b32_e32 v69, 0xffff0000, v58
	v_pk_add_f32 v[76:77], v[26:27], v[76:77]
	v_lshlrev_b32_e32 v62, 16, v63
	v_pk_mul_f32 v[68:69], v[76:77], v[68:69]
	v_pk_mul_f32 v[76:77], v[20:21], v[70:71]
	v_and_b32_e32 v63, 0xffff0000, v63
	v_pk_fma_f32 v[76:77], v[32:33], v[78:79], v[76:77]
	v_lshlrev_b32_e32 v78, 16, v64
	v_pk_fma_f32 v[76:77], v[24:25], v[62:63], v[76:77]
	v_and_b32_e32 v79, 0xffff0000, v64
	v_pk_fma_f32 v[82:83], v[10:11], v[94:95], v[82:83]
	v_lshlrev_b32_e32 v58, 16, v59
	v_and_b32_e32 v59, 0xffff0000, v59
	v_pk_add_f32 v[76:77], v[28:29], v[76:77]
	v_pk_fma_f32 v[82:83], v[2:3], v[78:79], v[82:83]
	v_pk_mul_f32 v[76:77], v[76:77], v[58:59]
	v_lshlrev_b32_e32 v58, 16, v60
	v_and_b32_e32 v59, 0xffff0000, v60
	v_pk_add_f32 v[82:83], v[14:15], v[82:83]
	v_lshlrev_b32_e32 v64, 16, v65
	v_pk_mul_f32 v[82:83], v[82:83], v[58:59]
	v_lshlrev_b32_e32 v58, 16, v61
	v_and_b32_e32 v59, 0xffff0000, v61
	v_pk_mul_f32 v[60:61], v[8:9], v[72:73]
	v_and_b32_e32 v65, 0xffff0000, v65
	v_pk_fma_f32 v[60:61], v[12:13], v[80:81], v[60:61]
	s_nop 0
	v_pk_fma_f32 v[60:61], v[4:5], v[64:65], v[60:61]
	s_nop 0
	v_pk_add_f32 v[60:61], v[16:17], v[60:61]
	s_nop 0
	v_pk_mul_f32 v[80:81], v[60:61], v[58:59]
	v_cvt_pk_bf16_f32 v58, v68, v69
	v_cvt_pk_bf16_f32 v59, v76, v77
	v_cvt_pk_bf16_f32 v60, v82, v83
	v_cvt_pk_bf16_f32 v61, v80, v81
	v_pk_mul_f32 v[68:69], v[18:19], v[66:67]
	global_store_dwordx4 v[104:105], v[58:61], off
	v_pk_fma_f32 v[68:69], v[30:31], v[74:75], v[68:69]
	v_pk_mul_f32 v[74:75], v[6:7], v[78:79]
	v_lshlrev_b32_e32 v58, 16, v54
	v_and_b32_e32 v59, 0xffff0000, v54
	v_pk_fma_f32 v[68:69], v[22:23], v[58:59], v[68:69]
	v_lshlrev_b32_e32 v60, 16, v50
	v_and_b32_e32 v61, 0xffff0000, v50
	v_pk_add_f32 v[68:69], v[26:27], v[68:69]
	v_lshlrev_b32_e32 v54, 16, v55
	v_pk_mul_f32 v[60:61], v[68:69], v[60:61]
	v_pk_mul_f32 v[68:69], v[20:21], v[62:63]
	v_and_b32_e32 v55, 0xffff0000, v55
	v_pk_fma_f32 v[68:69], v[32:33], v[70:71], v[68:69]
	v_lshlrev_b32_e32 v70, 16, v56
	v_pk_fma_f32 v[68:69], v[24:25], v[54:55], v[68:69]
	v_and_b32_e32 v71, 0xffff0000, v56
	v_pk_fma_f32 v[74:75], v[10:11], v[86:87], v[74:75]
	v_lshlrev_b32_e32 v50, 16, v51
	v_and_b32_e32 v51, 0xffff0000, v51
	v_pk_add_f32 v[68:69], v[28:29], v[68:69]
	v_pk_fma_f32 v[74:75], v[2:3], v[70:71], v[74:75]
	v_pk_mul_f32 v[68:69], v[68:69], v[50:51]
	v_lshlrev_b32_e32 v50, 16, v52
	v_and_b32_e32 v51, 0xffff0000, v52
	v_pk_add_f32 v[74:75], v[14:15], v[74:75]
	v_lshlrev_b32_e32 v56, 16, v57
	v_pk_mul_f32 v[74:75], v[74:75], v[50:51]
	v_lshlrev_b32_e32 v50, 16, v53
	v_and_b32_e32 v51, 0xffff0000, v53
	v_pk_mul_f32 v[52:53], v[8:9], v[64:65]
	v_and_b32_e32 v57, 0xffff0000, v57
	v_pk_fma_f32 v[52:53], v[12:13], v[72:73], v[52:53]
	s_nop 0
	v_pk_fma_f32 v[52:53], v[4:5], v[56:57], v[52:53]
	s_nop 0
	v_pk_add_f32 v[52:53], v[16:17], v[52:53]
	s_nop 0
	v_pk_mul_f32 v[72:73], v[52:53], v[50:51]
	v_cvt_pk_bf16_f32 v50, v60, v61
	v_cvt_pk_bf16_f32 v51, v68, v69
	v_cvt_pk_bf16_f32 v52, v74, v75
	v_cvt_pk_bf16_f32 v53, v72, v73
	v_pk_mul_f32 v[60:61], v[18:19], v[58:59]
	global_store_dwordx4 v[102:103], v[50:53], off
	v_pk_fma_f32 v[60:61], v[30:31], v[66:67], v[60:61]
	v_pk_mul_f32 v[66:67], v[6:7], v[70:71]
	v_lshlrev_b32_e32 v50, 16, v46
	v_and_b32_e32 v51, 0xffff0000, v46
	v_pk_fma_f32 v[60:61], v[22:23], v[50:51], v[60:61]
	v_lshlrev_b32_e32 v52, 16, v42
	v_and_b32_e32 v53, 0xffff0000, v42
	v_pk_add_f32 v[60:61], v[26:27], v[60:61]
	v_lshlrev_b32_e32 v46, 16, v47
	v_pk_mul_f32 v[52:53], v[60:61], v[52:53]
	v_pk_mul_f32 v[60:61], v[20:21], v[54:55]
	v_and_b32_e32 v47, 0xffff0000, v47
	v_pk_fma_f32 v[60:61], v[32:33], v[62:63], v[60:61]
	v_lshlrev_b32_e32 v62, 16, v48
	v_pk_fma_f32 v[60:61], v[24:25], v[46:47], v[60:61]
	v_and_b32_e32 v63, 0xffff0000, v48
	v_pk_fma_f32 v[66:67], v[10:11], v[78:79], v[66:67]
	v_lshlrev_b32_e32 v42, 16, v43
	v_and_b32_e32 v43, 0xffff0000, v43
	v_pk_add_f32 v[60:61], v[28:29], v[60:61]
	v_pk_fma_f32 v[66:67], v[2:3], v[62:63], v[66:67]
	v_pk_mul_f32 v[60:61], v[60:61], v[42:43]
	v_lshlrev_b32_e32 v42, 16, v44
	v_and_b32_e32 v43, 0xffff0000, v44
	v_pk_add_f32 v[66:67], v[14:15], v[66:67]
	v_lshlrev_b32_e32 v48, 16, v49
	v_pk_mul_f32 v[66:67], v[66:67], v[42:43]
	v_lshlrev_b32_e32 v42, 16, v45
	v_and_b32_e32 v43, 0xffff0000, v45
	v_pk_mul_f32 v[44:45], v[8:9], v[56:57]
	v_and_b32_e32 v49, 0xffff0000, v49
	v_pk_fma_f32 v[44:45], v[12:13], v[64:65], v[44:45]
	v_pk_mul_f32 v[18:19], v[18:19], v[50:51]
	v_pk_fma_f32 v[44:45], v[4:5], v[48:49], v[44:45]
	v_pk_fma_f32 v[18:19], v[30:31], v[58:59], v[18:19]
	v_pk_add_f32 v[44:45], v[16:17], v[44:45]
	v_pk_mul_f32 v[20:21], v[20:21], v[46:47]
	v_pk_mul_f32 v[64:65], v[44:45], v[42:43]
	v_cvt_pk_bf16_f32 v42, v52, v53
	v_cvt_pk_bf16_f32 v43, v60, v61
	v_cvt_pk_bf16_f32 v44, v66, v67
	v_cvt_pk_bf16_f32 v45, v64, v65
	global_store_dwordx4 v[100:101], v[42:45], off
	v_pk_fma_f32 v[20:21], v[32:33], v[54:55], v[20:21]
	v_pk_mul_f32 v[6:7], v[6:7], v[62:63]
	v_lshlrev_b32_e32 v42, 16, v34
	v_and_b32_e32 v43, 0xffff0000, v34
	v_pk_fma_f32 v[18:19], v[22:23], v[42:43], v[18:19]
	v_lshlrev_b32_e32 v22, 16, v35
	v_and_b32_e32 v23, 0xffff0000, v35
	v_pk_fma_f32 v[20:21], v[24:25], v[22:23], v[20:21]
	v_lshlrev_b32_e32 v22, 16, v36
	v_and_b32_e32 v23, 0xffff0000, v36
	v_pk_fma_f32 v[6:7], v[10:11], v[70:71], v[6:7]
	v_lshlrev_b32_e32 v24, 16, v40
	v_pk_fma_f32 v[2:3], v[2:3], v[22:23], v[6:7]
	v_and_b32_e32 v25, 0xffff0000, v40
	v_pk_add_f32 v[2:3], v[14:15], v[2:3]
	v_pk_mul_f32 v[8:9], v[8:9], v[48:49]
	v_pk_mul_f32 v[6:7], v[2:3], v[24:25]
	v_lshlrev_b32_e32 v2, 16, v37
	v_and_b32_e32 v3, 0xffff0000, v37
	v_pk_fma_f32 v[8:9], v[12:13], v[56:57], v[8:9]
	v_lshlrev_b32_e32 v44, 16, v38
	v_pk_fma_f32 v[2:3], v[4:5], v[2:3], v[8:9]
	v_and_b32_e32 v45, 0xffff0000, v38
	v_pk_add_f32 v[18:19], v[26:27], v[18:19]
	v_lshlrev_b32_e32 v26, 16, v39
	v_and_b32_e32 v27, 0xffff0000, v39
	v_pk_add_f32 v[20:21], v[28:29], v[20:21]
	v_lshlrev_b32_e32 v10, 16, v41
	v_and_b32_e32 v11, 0xffff0000, v41
	v_pk_add_f32 v[2:3], v[16:17], v[2:3]
	v_pk_mul_f32 v[18:19], v[18:19], v[44:45]
	v_pk_mul_f32 v[20:21], v[20:21], v[26:27]
	v_pk_mul_f32 v[8:9], v[2:3], v[10:11]
	v_cvt_pk_bf16_f32 v2, v18, v19
	v_cvt_pk_bf16_f32 v3, v20, v21
	v_cvt_pk_bf16_f32 v4, v6, v7
	v_cvt_pk_bf16_f32 v5, v8, v9
	global_store_dwordx4 v[98:99], v[2:5], off
	s_branch .LBB0_516
.LBB0_513:
.LBB0_514:
.LBB0_516:
	s_cmp_gt_i32 s89, 3
	s_cselect_b64 s[2:3], -1, 0
	s_and_b64 s[0:1], s[8:9], s[2:3]
	s_andn2_b64 vcc, exec, s[0:1]
	s_cbranch_vccnz .LBB0_570
	s_waitcnt vmcnt(0)
	s_waitcnt vmcnt(0)
	s_barrier
	s_and_saveexec_b64 s[4:5], s[84:85]
	s_cbranch_execz .LBB0_569
	s_add_u32 s98, s76, 0x3400
	s_addc_u32 s99, s77, 0
	v_mov_b32_e32 v2, 0
	s_mov_b32 s100, 0
.Lsp2_poll:
	global_load_dword v3, v2, s[98:99] sc1
	s_waitcnt vmcnt(0)
	v_readfirstlane_b32 s0, v3
	s_cmp_ge_u32 s0, s101
	s_cbranch_scc1 .Lsp2_go
	s_sleep 1
	s_add_i32 s100, s100, 1
	s_cmp_lt_u32 s100, 0x100000
	s_cbranch_scc1 .Lsp2_poll
.Lsp2_go:
	buffer_inv sc1
	s_waitcnt vmcnt(0)

.LBB0_852:
	s_or_b64 exec, exec, s[12:13]
	v_cvt_f32_u32_e32 v6, v4
	s_waitcnt vmcnt(0)
	v_readfirstlane_b32 s0, v5
	v_sub_u32_e32 v5, 0, v4
	v_rcp_iflag_f32_e32 v6, v6
	v_add_u32_e32 v7, s0, v3
	v_mul_f32_e32 v6, 0x4f7ffffe, v6
	v_cvt_u32_f32_e32 v6, v6
	v_mul_lo_u32 v3, v5, v6
	v_mul_hi_u32 v3, v6, v3
	v_add_u32_e32 v3, v6, v3
	v_mul_hi_u32 v3, v7, v3
	v_mul_lo_u32 v5, v3, v4
	v_sub_u32_e32 v5, v7, v5
	v_add_u32_e32 v6, 1, v3
	v_cmp_ge_u32_e32 vcc, v5, v4
	s_nop 1
	v_cndmask_b32_e32 v3, v3, v6, vcc
	v_sub_u32_e32 v6, v5, v4
	v_cndmask_b32_e32 v5, v5, v6, vcc
	v_add_u32_e32 v6, 1, v3
	v_cmp_ge_u32_e32 vcc, v5, v4
	v_add_u32_e32 v5, 1, v7
	s_nop 0
	v_cndmask_b32_e32 v3, v3, v6, vcc
	v_mul_lo_u32 v6, v4, v3
	v_add_u32_e32 v4, v6, v4
	v_cmp_ne_u32_e32 vcc, v5, v4
	s_and_saveexec_b64 s[0:1], vcc
	s_xor_b64 s[10:11], exec, s[0:1]
	s_cbranch_execz .LBB0_866
	s_waitcnt lgkmcnt(0)
	v_add_u32_e32 v249, 1, v3
	v_mul_lo_u32 v249, v249, v2
	s_add_u32 s98, s76, 0x3400
	s_addc_u32 s99, s77, 0
	v_mov_b32_e32 v2, 0
	global_load_dword v2, v2, s[98:99] sc1
	s_add_u32 s14, s8, 0x2400
	s_addc_u32 s15, s9, 0
	s_waitcnt vmcnt(0)
	v_cmp_lt_u32_e32 vcc, v2, v249
	s_and_saveexec_b64 s[12:13], vcc
	s_cbranch_execz .LBB0_865
	s_mov_b32 s0, 1
	s_mov_b64 s[16:17], 0
	v_mov_b32_e32 v2, 0
	s_branch .LBB0_856

.LBB0_858:
	global_load_dword v4, v2, s[98:99] sc1
	s_add_i32 s0, s0, 1
	s_mov_b64 s[22:23], -1
	s_waitcnt vmcnt(0)
	v_cmp_ge_u32_e32 vcc, v4, v249
	s_orn2_b64 s[20:21], vcc, exec
	s_branch .LBB0_855
